# hy_merge and hy_prep tiles hand-written: wave = consecutive time steps, lane = adjacent channels, all loads up-front, DPP row reduction, no LDS transpose; f32 math unchanged
# speedup vs baseline: 1.0583x; 1.0313x over previous
; __device__ __forceinline__ float bf2f(bf16_t h) { return __uint_as_float(((unsigned)h) << 16); }
; __device__ void hy_prep_tile(unsigned char* lds, const Params& p, int l, int b, int ck) {
;     ...
;   const bool isctx = ck < 4;
;   const int L = isctx ? 256 : 2048;
;   const int t0 = isctx ? ck * 64 : (ck - 4) * 64;
;   const int rowbase = isctx ? (NLAT + b * 256) : (b * 2048);
;   const int posoff = isctx ? 2048 : 0;
;   {
;     const int c = tid & 255, half = tid >> 8;
;     const float* wc = p.in[9] + (size_t)l * 3 * 768;
;     const float a0 = wc[256 + c], a1 = wc[768 + 256 + c], a2 = wc[1536 + 256 + c];
;     const float v0 = wc[512 + c], v1 = wc[768 + 512 + c], v2 = wc[1536 + 512 + c];
;     const int ts = t0 + half * 32;
;     float xp, xc, xn, vp, vc, vn;
;     { const int tq = ts - 1 >= 0 ? ts - 1 : 0; const float mk = ts - 1 >= 0 ? 1.f : 0.f;
;       xp = mk * bf2f(z[(size_t)(rowbase + tq) * ZS + 256 + c]); vp = mk * bf2f(z[(size_t)(rowbase + tq) * ZS + 512 + c]); }
;     xc = bf2f(z[(size_t)(rowbase + ts) * ZS + 256 + c]); vc = bf2f(z[(size_t)(rowbase + ts) * ZS + 512 + c]);
; #pragma unroll 8
;     for (int q = 0; q < 32; ++q) {
;       const int tp = ts + q;
;       { const int tq = tp + 1 < L ? tp + 1 : L - 1; const float mk = tp + 1 < L ? 1.f : 0.f;
;         xn = mk * bf2f(z[(size_t)(rowbase + tq) * ZS + 256 + c]); vn = mk * bf2f(z[(size_t)(rowbase + tq) * ZS + 512 + c]); }
.LBB0_323:
	s_cmpk_gt_i32 s20, 0x23f
	s_mov_b64 s[0:1], -1
	s_cbranch_scc0 .LBB0_331
	s_cmpk_gt_u32 s20, 0x6bf
	s_cbranch_scc0 .LBB0_326
	s_add_i32 s0, s20, 0xf940
	s_and_b32 s1, s0, 0xffff
	s_mul_i32 s1, s1, 0xe38f
	s_lshr_b32 s1, s1, 21
	s_mul_i32 s2, s1, 36
	s_sub_i32 s0, s0, s2
	s_and_b32 s2, s0, 0xffff
	s_cmp_lt_u32 s2, 4
	s_cselect_b64 s[2:3], -1, 0
	s_and_b32 s0, s0, 0xffff
	s_lshl_b32 s4, s0, 6
	s_add_i32 s5, s4, 0xffffff00
	s_lshl_b32 s6, s1, 8
	s_add_i32 s6, s6, 0x4000
	s_lshl_b32 s7, s1, 11
	s_movk_i32 s8, 0x100
	s_movk_i32 s9, 0x800
	s_cmp_lt_u32 s0, 4
	s_cselect_b32 s44, s4, s5
	s_cselect_b32 s45, s8, s9
	s_cselect_b32 s46, s6, s7
	s_cselect_b32 s47, s9, 0
	v_readfirstlane_b32 s48, v195
	v_and_b32_e32 v50, 0xff, v195
	v_readlane_b32 s58, v251, 31
	v_readlane_b32 s59, v251, 32
	s_lshr_b32 s48, s48, 8
	s_lshl_b32 s49, s48, 5
	s_add_i32 s49, s49, s44
	s_mul_i32 s4, s1, 0x1200
	s_add_i32 s5, s47, s49
	s_lshl_b32 s5, s5, 1
	s_add_i32 s4, s4, s5
	s_add_u32 s58, s58, s4
	s_addc_u32 s59, s59, 0
	s_add_i32 s4, s46, s49
	s_mul_i32 s50, s4, 0x1a00
	s_add_i32 s4, s49, -1
	s_max_i32 s4, s4, 0
	s_add_i32 s4, s4, s46
	s_mul_i32 s51, s4, 0x1a00
	s_add_i32 s4, s49, 32
	s_add_i32 s5, s45, -1
	s_min_i32 s4, s4, s5
	s_add_i32 s4, s4, s46
	s_mul_i32 s5, s4, 0x1a00
	v_lshlrev_b32_e32 v55, 1, v50
	v_lshlrev_b32_e32 v53, 2, v50
	s_mov_b32 s6, 0x9000
	v_mul_lo_u32 v54, v50, s6
	v_add_u32_e32 v51, s50, v55
	v_add_u32_e32 v52, s51, v55
	v_add_u32_e32 v56, 0xc00, v53
	v_add_u32_e32 v57, 0x1800, v53
	global_load_dword v199, v53, s[14:15] offset:1024
	global_load_dword v202, v53, s[14:15] offset:2048
	global_load_dword v200, v56, s[14:15] offset:1024
	global_load_dword v203, v56, s[14:15] offset:2048
	global_load_dword v201, v57, s[14:15] offset:1024
	global_load_dword v204, v57, s[14:15] offset:2048
	global_load_ushort v0, v52, s[88:89] offset:512
	global_load_ushort v154, v52, s[88:89] offset:1024
	global_load_ushort v1, v51, s[88:89] offset:512
	global_load_ushort v155, v51, s[88:89] offset:1024
	v_add_u32_e32 v51, 0x1a00, v51
	global_load_ushort v2, v51, s[88:89] offset:512
	global_load_ushort v156, v51, s[88:89] offset:1024
	v_add_u32_e32 v51, 0x1a00, v51
	global_load_ushort v3, v51, s[88:89] offset:512
	global_load_ushort v157, v51, s[88:89] offset:1024
	v_add_u32_e32 v51, 0x1a00, v51
	global_load_ushort v4, v51, s[88:89] offset:512
	global_load_ushort v158, v51, s[88:89] offset:1024
	v_add_u32_e32 v51, 0x1a00, v51
	global_load_ushort v5, v51, s[88:89] offset:512
	global_load_ushort v159, v51, s[88:89] offset:1024
	v_add_u32_e32 v51, 0x1a00, v51
	global_load_ushort v6, v51, s[88:89] offset:512
	global_load_ushort v160, v51, s[88:89] offset:1024
	v_add_u32_e32 v51, 0x1a00, v51
	global_load_ushort v7, v51, s[88:89] offset:512
	global_load_ushort v161, v51, s[88:89] offset:1024
	v_add_u32_e32 v51, 0x1a00, v51
	global_load_ushort v8, v51, s[88:89] offset:512
	global_load_ushort v162, v51, s[88:89] offset:1024
	v_add_u32_e32 v51, 0x1a00, v51
	global_load_ushort v9, v51, s[88:89] offset:512
	global_load_ushort v163, v51, s[88:89] offset:1024
	v_add_u32_e32 v51, 0x1a00, v51
	global_load_ushort v10, v51, s[88:89] offset:512
	global_load_ushort v164, v51, s[88:89] offset:1024
	v_add_u32_e32 v51, 0x1a00, v51
	global_load_ushort v11, v51, s[88:89] offset:512
	global_load_ushort v165, v51, s[88:89] offset:1024
	v_add_u32_e32 v51, 0x1a00, v51
	global_load_ushort v12, v51, s[88:89] offset:512
	global_load_ushort v166, v51, s[88:89] offset:1024
	v_add_u32_e32 v51, 0x1a00, v51
	global_load_ushort v13, v51, s[88:89] offset:512
	global_load_ushort v167, v51, s[88:89] offset:1024
	v_add_u32_e32 v51, 0x1a00, v51
	global_load_ushort v14, v51, s[88:89] offset:512
	global_load_ushort v168, v51, s[88:89] offset:1024
	v_add_u32_e32 v51, 0x1a00, v51
	global_load_ushort v15, v51, s[88:89] offset:512
	global_load_ushort v169, v51, s[88:89] offset:1024
	v_add_u32_e32 v51, 0x1a00, v51
	global_load_ushort v16, v51, s[88:89] offset:512
	global_load_ushort v170, v51, s[88:89] offset:1024
	v_add_u32_e32 v51, 0x1a00, v51
	global_load_ushort v17, v51, s[88:89] offset:512
	global_load_ushort v171, v51, s[88:89] offset:1024
	v_add_u32_e32 v51, 0x1a00, v51
	global_load_ushort v18, v51, s[88:89] offset:512
	global_load_ushort v172, v51, s[88:89] offset:1024
	v_add_u32_e32 v51, 0x1a00, v51
	global_load_ushort v19, v51, s[88:89] offset:512
	global_load_ushort v173, v51, s[88:89] offset:1024
	v_add_u32_e32 v51, 0x1a00, v51
	global_load_ushort v20, v51, s[88:89] offset:512
	global_load_ushort v174, v51, s[88:89] offset:1024
	v_add_u32_e32 v51, 0x1a00, v51
	global_load_ushort v21, v51, s[88:89] offset:512
	global_load_ushort v175, v51, s[88:89] offset:1024
	v_add_u32_e32 v51, 0x1a00, v51
	global_load_ushort v22, v51, s[88:89] offset:512
	global_load_ushort v176, v51, s[88:89] offset:1024
	v_add_u32_e32 v51, 0x1a00, v51
	global_load_ushort v23, v51, s[88:89] offset:512
	global_load_ushort v177, v51, s[88:89] offset:1024
	v_add_u32_e32 v51, 0x1a00, v51
	global_load_ushort v24, v51, s[88:89] offset:512
	global_load_ushort v178, v51, s[88:89] offset:1024
	v_add_u32_e32 v51, 0x1a00, v51
	global_load_ushort v25, v51, s[88:89] offset:512
	global_load_ushort v179, v51, s[88:89] offset:1024
	v_add_u32_e32 v51, 0x1a00, v51
	v_add_u32_e32 v50, s5, v55
	s_cmp_ge_i32 s49, 1
	s_cselect_b64 s[60:61], -1, 0
	s_add_i32 s4, s49, 32
	s_cmp_lt_i32 s4, s45
	s_cselect_b64 s[6:7], -1, 0
	s_waitcnt vmcnt(32)
; __device__ __forceinline__ bf16_t f2bf(float f) { return (bf16_t)(pack2(f, 0.f) & 0xffffu); }
; __device__ __forceinline__ float bf2f(bf16_t h) { return __uint_as_float(((unsigned)h) << 16); }
; __device__ void hy_prep_tile(unsigned char* lds, const Params& p, int l, int b, int ck) {
;     ...
;     for (int q = 0; q < 32; ++q) {
;       const int tp = ts + q;
;       { const int tq = tp + 1 < L ? tp + 1 : L - 1; const float mk = tp + 1 < L ? 1.f : 0.f;
;         xn = mk * bf2f(z[(size_t)(rowbase + tq) * ZS + 256 + c]); vn = mk * bf2f(z[(size_t)(rowbase + tq) * ZS + 512 + c]); }
;       const float x1 = a0 * xp + a1 * xc + a2 * xn;
;       const float vv = v0 * vp + v1 * vc + v2 * vn;
;       uL[c * 66 + half * 32 + q] = f2bf(x1 * vv);
;       xp = xc; xc = xn; vp = vc; vc = vn;
;     }
	v_lshlrev_b32_e32 v0, 16, v0
	v_lshlrev_b32_e32 v154, 16, v154
	v_lshlrev_b32_e32 v1, 16, v1
	v_lshlrev_b32_e32 v155, 16, v155
	v_lshlrev_b32_e32 v2, 16, v2
	v_lshlrev_b32_e32 v156, 16, v156
	v_lshlrev_b32_e32 v3, 16, v3
	v_lshlrev_b32_e32 v157, 16, v157
	v_lshlrev_b32_e32 v4, 16, v4
	v_lshlrev_b32_e32 v158, 16, v158
	v_lshlrev_b32_e32 v5, 16, v5
	v_lshlrev_b32_e32 v159, 16, v159
	v_lshlrev_b32_e32 v6, 16, v6
	v_lshlrev_b32_e32 v160, 16, v160
	v_lshlrev_b32_e32 v7, 16, v7
	v_lshlrev_b32_e32 v161, 16, v161
	v_lshlrev_b32_e32 v8, 16, v8
	v_lshlrev_b32_e32 v162, 16, v162
	v_lshlrev_b32_e32 v9, 16, v9
	v_lshlrev_b32_e32 v163, 16, v163
	global_load_ushort v26, v51, s[88:89] offset:512
	global_load_ushort v180, v51, s[88:89] offset:1024
	v_add_u32_e32 v51, 0x1a00, v51
	global_load_ushort v27, v51, s[88:89] offset:512
	global_load_ushort v181, v51, s[88:89] offset:1024
	v_add_u32_e32 v51, 0x1a00, v51
	global_load_ushort v28, v51, s[88:89] offset:512
	global_load_ushort v182, v51, s[88:89] offset:1024
	v_add_u32_e32 v51, 0x1a00, v51
	global_load_ushort v29, v51, s[88:89] offset:512
	global_load_ushort v183, v51, s[88:89] offset:1024
	v_add_u32_e32 v51, 0x1a00, v51
	global_load_ushort v30, v51, s[88:89] offset:512
	global_load_ushort v184, v51, s[88:89] offset:1024
	v_add_u32_e32 v51, 0x1a00, v51
	global_load_ushort v31, v51, s[88:89] offset:512
	global_load_ushort v185, v51, s[88:89] offset:1024
	v_add_u32_e32 v51, 0x1a00, v51
	global_load_ushort v32, v51, s[88:89] offset:512
	global_load_ushort v186, v51, s[88:89] offset:1024
	global_load_ushort v33, v50, s[88:89] offset:512
	global_load_ushort v187, v50, s[88:89] offset:1024
	v_cndmask_b32_e64 v0, 0, v0, s[60:61]
	v_cndmask_b32_e64 v154, 0, v154, s[60:61]
	v_mul_f32_e32 v55, v199, v0
	v_mul_f32_e32 v52, v202, v154
	v_fmac_f32_e32 v55, v200, v1
	v_fmac_f32_e32 v52, v203, v155
	v_fmac_f32_e32 v55, v201, v2
	v_fmac_f32_e32 v52, v204, v156
	v_mul_f32_e32 v56, v55, v52
	v_mul_f32_e32 v55, v199, v1
	v_mul_f32_e32 v52, v202, v155
	v_fmac_f32_e32 v55, v200, v2
	v_fmac_f32_e32 v52, v203, v156
	v_fmac_f32_e32 v55, v201, v3
	v_fmac_f32_e32 v52, v204, v157
	v_mul_f32_e32 v57, v55, v52
	v_cvt_pk_bf16_f32 v34, v56, v57
	v_mul_f32_e32 v55, v199, v2
	v_mul_f32_e32 v52, v202, v156
	v_fmac_f32_e32 v55, v200, v3
	v_fmac_f32_e32 v52, v203, v157
	v_fmac_f32_e32 v55, v201, v4
	v_fmac_f32_e32 v52, v204, v158
	v_mul_f32_e32 v56, v55, v52
	v_mul_f32_e32 v55, v199, v3
	v_mul_f32_e32 v52, v202, v157
	v_fmac_f32_e32 v55, v200, v4
	v_fmac_f32_e32 v52, v203, v158
	v_fmac_f32_e32 v55, v201, v5
	v_fmac_f32_e32 v52, v204, v159
	v_mul_f32_e32 v57, v55, v52
	v_cvt_pk_bf16_f32 v35, v56, v57
	v_mul_f32_e32 v55, v199, v4
	v_mul_f32_e32 v52, v202, v158
	v_fmac_f32_e32 v55, v200, v5
	v_fmac_f32_e32 v52, v203, v159
	v_fmac_f32_e32 v55, v201, v6
	v_fmac_f32_e32 v52, v204, v160
	v_mul_f32_e32 v56, v55, v52
	v_mul_f32_e32 v55, v199, v5
	v_mul_f32_e32 v52, v202, v159
	v_fmac_f32_e32 v55, v200, v6
	v_fmac_f32_e32 v52, v203, v160
	v_fmac_f32_e32 v55, v201, v7
	v_fmac_f32_e32 v52, v204, v161
	v_mul_f32_e32 v57, v55, v52
	v_cvt_pk_bf16_f32 v36, v56, v57
	v_mul_f32_e32 v55, v199, v6
	v_mul_f32_e32 v52, v202, v160
	v_fmac_f32_e32 v55, v200, v7
	v_fmac_f32_e32 v52, v203, v161
	v_fmac_f32_e32 v55, v201, v8
	v_fmac_f32_e32 v52, v204, v162
	v_mul_f32_e32 v56, v55, v52
	v_mul_f32_e32 v55, v199, v7
	v_mul_f32_e32 v52, v202, v161
	v_fmac_f32_e32 v55, v200, v8
	v_fmac_f32_e32 v52, v203, v162
	v_fmac_f32_e32 v55, v201, v9
	v_fmac_f32_e32 v52, v204, v163
	v_mul_f32_e32 v57, v55, v52
	v_cvt_pk_bf16_f32 v37, v56, v57
	s_waitcnt vmcnt(32)
	v_lshlrev_b32_e32 v10, 16, v10
	v_lshlrev_b32_e32 v164, 16, v164
	v_lshlrev_b32_e32 v11, 16, v11
	v_lshlrev_b32_e32 v165, 16, v165
	v_lshlrev_b32_e32 v12, 16, v12
	v_lshlrev_b32_e32 v166, 16, v166
	v_lshlrev_b32_e32 v13, 16, v13
	v_lshlrev_b32_e32 v167, 16, v167
	v_lshlrev_b32_e32 v14, 16, v14
	v_lshlrev_b32_e32 v168, 16, v168
	v_lshlrev_b32_e32 v15, 16, v15
	v_lshlrev_b32_e32 v169, 16, v169
	v_lshlrev_b32_e32 v16, 16, v16
	v_lshlrev_b32_e32 v170, 16, v170
	v_lshlrev_b32_e32 v17, 16, v17
	v_lshlrev_b32_e32 v171, 16, v171
	v_mul_f32_e32 v55, v199, v8
	v_mul_f32_e32 v52, v202, v162
	v_fmac_f32_e32 v55, v200, v9
	v_fmac_f32_e32 v52, v203, v163
	v_fmac_f32_e32 v55, v201, v10
	v_fmac_f32_e32 v52, v204, v164
	v_mul_f32_e32 v56, v55, v52
	v_mul_f32_e32 v55, v199, v9
	v_mul_f32_e32 v52, v202, v163
	v_fmac_f32_e32 v55, v200, v10
	v_fmac_f32_e32 v52, v203, v164
	v_fmac_f32_e32 v55, v201, v11
	v_fmac_f32_e32 v52, v204, v165
	v_mul_f32_e32 v57, v55, v52
	v_cvt_pk_bf16_f32 v38, v56, v57
	v_mul_f32_e32 v55, v199, v10
	v_mul_f32_e32 v52, v202, v164
	v_fmac_f32_e32 v55, v200, v11
	v_fmac_f32_e32 v52, v203, v165
	v_fmac_f32_e32 v55, v201, v12
	v_fmac_f32_e32 v52, v204, v166
	v_mul_f32_e32 v56, v55, v52
	v_mul_f32_e32 v55, v199, v11
	v_mul_f32_e32 v52, v202, v165
	v_fmac_f32_e32 v55, v200, v12
	v_fmac_f32_e32 v52, v203, v166
	v_fmac_f32_e32 v55, v201, v13
	v_fmac_f32_e32 v52, v204, v167
	v_mul_f32_e32 v57, v55, v52
	v_cvt_pk_bf16_f32 v39, v56, v57
	v_mul_f32_e32 v55, v199, v12
	v_mul_f32_e32 v52, v202, v166
	v_fmac_f32_e32 v55, v200, v13
	v_fmac_f32_e32 v52, v203, v167
	v_fmac_f32_e32 v55, v201, v14
	v_fmac_f32_e32 v52, v204, v168
	v_mul_f32_e32 v56, v55, v52
	v_mul_f32_e32 v55, v199, v13
	v_mul_f32_e32 v52, v202, v167
	v_fmac_f32_e32 v55, v200, v14
	v_fmac_f32_e32 v52, v203, v168
	v_fmac_f32_e32 v55, v201, v15
	v_fmac_f32_e32 v52, v204, v169
	v_mul_f32_e32 v57, v55, v52
	v_cvt_pk_bf16_f32 v40, v56, v57
	v_mul_f32_e32 v55, v199, v14
	v_mul_f32_e32 v52, v202, v168
	v_fmac_f32_e32 v55, v200, v15
	v_fmac_f32_e32 v52, v203, v169
	v_fmac_f32_e32 v55, v201, v16
	v_fmac_f32_e32 v52, v204, v170
	v_mul_f32_e32 v56, v55, v52
	v_mul_f32_e32 v55, v199, v15
	v_mul_f32_e32 v52, v202, v169
	v_fmac_f32_e32 v55, v200, v16
	v_fmac_f32_e32 v52, v203, v170
	v_fmac_f32_e32 v55, v201, v17
	v_fmac_f32_e32 v52, v204, v171
	v_mul_f32_e32 v57, v55, v52
	v_cvt_pk_bf16_f32 v41, v56, v57
	s_waitcnt vmcnt(16)
; __device__ __forceinline__ bf16_t f2bf(float f) { return (bf16_t)(pack2(f, 0.f) & 0xffffu); }
; __device__ __forceinline__ float bf2f(bf16_t h) { return __uint_as_float(((unsigned)h) << 16); }
; __device__ void hy_prep_tile(unsigned char* lds, const Params& p, int l, int b, int ck) {
;     ...
;     for (int q = 0; q < 32; ++q) {
;       const int tp = ts + q;
;       { const int tq = tp + 1 < L ? tp + 1 : L - 1; const float mk = tp + 1 < L ? 1.f : 0.f;
;         xn = mk * bf2f(z[(size_t)(rowbase + tq) * ZS + 256 + c]); vn = mk * bf2f(z[(size_t)(rowbase + tq) * ZS + 512 + c]); }
;       const float x1 = a0 * xp + a1 * xc + a2 * xn;
;       const float vv = v0 * vp + v1 * vc + v2 * vn;
;       uL[c * 66 + half * 32 + q] = f2bf(x1 * vv);
;       xp = xc; xc = xn; vp = vc; vc = vn;
;     }
;   }
;   __syncthreads();
;   {
;     const int c = tid >> 1, hf = tid & 1;
;     const unsigned* src = (const unsigned*)(uL + c * 66 + hf * 32);
;     uint4* dst = (uint4*)(uT + ((size_t)c * 8 + b) * LTOT + posoff + t0 + hf * 32);
; #pragma unroll
;     for (int q = 0; q < 4; ++q) {
;       uint4 u; u.x = src[q * 4 + 0]; u.y = src[q * 4 + 1]; u.z = src[q * 4 + 2]; u.w = src[q * 4 + 3];
;       dst[q] = u;
;     }
;   }
;   __syncthreads();
	v_lshlrev_b32_e32 v18, 16, v18
	v_lshlrev_b32_e32 v172, 16, v172
	v_lshlrev_b32_e32 v19, 16, v19
	v_lshlrev_b32_e32 v173, 16, v173
	v_lshlrev_b32_e32 v20, 16, v20
	v_lshlrev_b32_e32 v174, 16, v174
	v_lshlrev_b32_e32 v21, 16, v21
	v_lshlrev_b32_e32 v175, 16, v175
	v_lshlrev_b32_e32 v22, 16, v22
	v_lshlrev_b32_e32 v176, 16, v176
	v_lshlrev_b32_e32 v23, 16, v23
	v_lshlrev_b32_e32 v177, 16, v177
	v_lshlrev_b32_e32 v24, 16, v24
	v_lshlrev_b32_e32 v178, 16, v178
	v_lshlrev_b32_e32 v25, 16, v25
	v_lshlrev_b32_e32 v179, 16, v179
	v_mul_f32_e32 v55, v199, v16
	v_mul_f32_e32 v52, v202, v170
	v_fmac_f32_e32 v55, v200, v17
	v_fmac_f32_e32 v52, v203, v171
	v_fmac_f32_e32 v55, v201, v18
	v_fmac_f32_e32 v52, v204, v172
	v_mul_f32_e32 v56, v55, v52
	v_mul_f32_e32 v55, v199, v17
	v_mul_f32_e32 v52, v202, v171
	v_fmac_f32_e32 v55, v200, v18
	v_fmac_f32_e32 v52, v203, v172
	v_fmac_f32_e32 v55, v201, v19
	v_fmac_f32_e32 v52, v204, v173
	v_mul_f32_e32 v57, v55, v52
	v_cvt_pk_bf16_f32 v42, v56, v57
	v_mul_f32_e32 v55, v199, v18
	v_mul_f32_e32 v52, v202, v172
	v_fmac_f32_e32 v55, v200, v19
	v_fmac_f32_e32 v52, v203, v173
	v_fmac_f32_e32 v55, v201, v20
	v_fmac_f32_e32 v52, v204, v174
	v_mul_f32_e32 v56, v55, v52
	v_mul_f32_e32 v55, v199, v19
	v_mul_f32_e32 v52, v202, v173
	v_fmac_f32_e32 v55, v200, v20
	v_fmac_f32_e32 v52, v203, v174
	v_fmac_f32_e32 v55, v201, v21
	v_fmac_f32_e32 v52, v204, v175
	v_mul_f32_e32 v57, v55, v52
	v_cvt_pk_bf16_f32 v43, v56, v57
	v_mul_f32_e32 v55, v199, v20
	v_mul_f32_e32 v52, v202, v174
	v_fmac_f32_e32 v55, v200, v21
	v_fmac_f32_e32 v52, v203, v175
	v_fmac_f32_e32 v55, v201, v22
	v_fmac_f32_e32 v52, v204, v176
	v_mul_f32_e32 v56, v55, v52
	v_mul_f32_e32 v55, v199, v21
	v_mul_f32_e32 v52, v202, v175
	v_fmac_f32_e32 v55, v200, v22
	v_fmac_f32_e32 v52, v203, v176
	v_fmac_f32_e32 v55, v201, v23
	v_fmac_f32_e32 v52, v204, v177
	v_mul_f32_e32 v57, v55, v52
	v_cvt_pk_bf16_f32 v44, v56, v57
	v_mul_f32_e32 v55, v199, v22
	v_mul_f32_e32 v52, v202, v176
	v_fmac_f32_e32 v55, v200, v23
	v_fmac_f32_e32 v52, v203, v177
	v_fmac_f32_e32 v55, v201, v24
	v_fmac_f32_e32 v52, v204, v178
	v_mul_f32_e32 v56, v55, v52
	v_mul_f32_e32 v55, v199, v23
	v_mul_f32_e32 v52, v202, v177
	v_fmac_f32_e32 v55, v200, v24
	v_fmac_f32_e32 v52, v203, v178
	v_fmac_f32_e32 v55, v201, v25
	v_fmac_f32_e32 v52, v204, v179
	v_mul_f32_e32 v57, v55, v52
	v_cvt_pk_bf16_f32 v45, v56, v57
	s_waitcnt vmcnt(0)
	v_lshlrev_b32_e32 v26, 16, v26
	v_lshlrev_b32_e32 v180, 16, v180
	v_lshlrev_b32_e32 v27, 16, v27
	v_lshlrev_b32_e32 v181, 16, v181
	v_lshlrev_b32_e32 v28, 16, v28
	v_lshlrev_b32_e32 v182, 16, v182
	v_lshlrev_b32_e32 v29, 16, v29
	v_lshlrev_b32_e32 v183, 16, v183
	v_lshlrev_b32_e32 v30, 16, v30
	v_lshlrev_b32_e32 v184, 16, v184
	v_lshlrev_b32_e32 v31, 16, v31
	v_lshlrev_b32_e32 v185, 16, v185
	v_lshlrev_b32_e32 v32, 16, v32
	v_lshlrev_b32_e32 v186, 16, v186
	v_lshlrev_b32_e32 v33, 16, v33
	v_lshlrev_b32_e32 v187, 16, v187
	v_cndmask_b32_e64 v33, 0, v33, s[6:7]
	v_cndmask_b32_e64 v187, 0, v187, s[6:7]
	v_mul_f32_e32 v55, v199, v24
	v_mul_f32_e32 v52, v202, v178
	v_fmac_f32_e32 v55, v200, v25
	v_fmac_f32_e32 v52, v203, v179
	v_fmac_f32_e32 v55, v201, v26
	v_fmac_f32_e32 v52, v204, v180
	v_mul_f32_e32 v56, v55, v52
	v_mul_f32_e32 v55, v199, v25
	v_mul_f32_e32 v52, v202, v179
	v_fmac_f32_e32 v55, v200, v26
	v_fmac_f32_e32 v52, v203, v180
	v_fmac_f32_e32 v55, v201, v27
	v_fmac_f32_e32 v52, v204, v181
	v_mul_f32_e32 v57, v55, v52
	v_cvt_pk_bf16_f32 v46, v56, v57
	v_mul_f32_e32 v55, v199, v26
	v_mul_f32_e32 v52, v202, v180
	v_fmac_f32_e32 v55, v200, v27
	v_fmac_f32_e32 v52, v203, v181
	v_fmac_f32_e32 v55, v201, v28
	v_fmac_f32_e32 v52, v204, v182
	v_mul_f32_e32 v56, v55, v52
	v_mul_f32_e32 v55, v199, v27
	v_mul_f32_e32 v52, v202, v181
	v_fmac_f32_e32 v55, v200, v28
	v_fmac_f32_e32 v52, v203, v182
	v_fmac_f32_e32 v55, v201, v29
	v_fmac_f32_e32 v52, v204, v183
	v_mul_f32_e32 v57, v55, v52
	v_cvt_pk_bf16_f32 v47, v56, v57
	v_mul_f32_e32 v55, v199, v28
	v_mul_f32_e32 v52, v202, v182
	v_fmac_f32_e32 v55, v200, v29
	v_fmac_f32_e32 v52, v203, v183
	v_fmac_f32_e32 v55, v201, v30
	v_fmac_f32_e32 v52, v204, v184
	v_mul_f32_e32 v56, v55, v52
	v_mul_f32_e32 v55, v199, v29
	v_mul_f32_e32 v52, v202, v183
	v_fmac_f32_e32 v55, v200, v30
	v_fmac_f32_e32 v52, v203, v184
	v_fmac_f32_e32 v55, v201, v31
	v_fmac_f32_e32 v52, v204, v185
	v_mul_f32_e32 v57, v55, v52
	v_cvt_pk_bf16_f32 v48, v56, v57
	v_mul_f32_e32 v55, v199, v30
	v_mul_f32_e32 v52, v202, v184
	v_fmac_f32_e32 v55, v200, v31
	v_fmac_f32_e32 v52, v203, v185
	v_fmac_f32_e32 v55, v201, v32
	v_fmac_f32_e32 v52, v204, v186
	v_mul_f32_e32 v56, v55, v52
	v_mul_f32_e32 v55, v199, v31
	v_mul_f32_e32 v52, v202, v185
	v_fmac_f32_e32 v55, v200, v32
	v_fmac_f32_e32 v52, v203, v186
	v_fmac_f32_e32 v55, v201, v33
	v_fmac_f32_e32 v52, v204, v187
	v_mul_f32_e32 v57, v55, v52
	v_cvt_pk_bf16_f32 v49, v56, v57
	global_store_dwordx4 v54, v[34:37], s[58:59]
	global_store_dwordx4 v54, v[38:41], s[58:59] offset:16
	global_store_dwordx4 v54, v[42:45], s[58:59] offset:32
	global_store_dwordx4 v54, v[46:49], s[58:59] offset:48
	s_mov_b64 s[0:1], 0
	s_barrier

; __device__ __forceinline__ float bf2f(bf16_t h) { return __uint_as_float(((unsigned)h) << 16); }
; __device__ void hy_merge_tile(unsigned char* lds, const Params& p, int l, int b, int ck) {
;     ...
;   const bool isctx = ck < 4;
;   const int L = isctx ? 256 : 2048;
;   const int t0 = isctx ? ck * 64 : (ck - 4) * 64;
;   const int rowbase = isctx ? (NLAT + b * 256) : (b * 2048);
;   const int posoff = isctx ? 2048 : 0;
; #pragma unroll
;   for (int i = 0; i < 4; ++i) {
;     const int id = tid + 512 * i;
;     const int c = id >> 3, q = id & 7;
;     *(uint4*)(yL + c * 72 + q * 8) = *(const uint4*)(ycv + ((size_t)c * 8 + b) * LTOT + posoff + t0 + q * 8);
;   }
;   __syncthreads();
;   const float* wc = p.in[9] + (size_t)l * 3 * 768;
;   const float* gm = p.in[24] + (size_t)l * 1024;
; #pragma unroll 4
;   for (int q = 0; q < 8; ++q) {
;     const int tt = w + 8 * q;
;     const int tp = t0 + tt;
; #pragma unroll
;     for (int gi = 0; gi < 4; ++gi) {
;       const int c = gi * 64 + lane;
;       const int tm1 = tp - 1 >= 0 ? tp - 1 : 0, tp1 = tp + 1 < L ? tp + 1 : L - 1;
;       const float za = bf2f(z[(size_t)(rowbase + tm1) * ZS + c]);
;       const float zb = bf2f(z[(size_t)(rowbase + tp) * ZS + c]);
;       const float zc = bf2f(z[(size_t)(rowbase + tp1) * ZS + c]);
;       float x0 = wc[768 + c] * zb;
;       x0 += (tp - 1 >= 0 ? wc[c] : 0.f) * za;
;       x0 += (tp + 1 < L ? wc[1536 + c] : 0.f) * zc;
;       const float v = x0 * bf2f(yL[c * 72 + tt]);
.LBB0_639:
	s_cmp_ge_i32 s13, s30
	s_mov_b64 s[0:1], -1
	s_cbranch_scc0 .LBB0_714
	v_readlane_b32 s0, v254, 23
	s_cmp_ge_i32 s13, s0
	s_mov_b64 s[0:1], -1
	s_cbranch_scc0 .LBB0_708
	v_readlane_b32 s0, v254, 23
	s_sub_i32 s0, s13, s0
	v_readlane_b32 s1, v254, 14
	s_mul_hi_u32 s1, s0, s1
	v_readlane_b32 s5, v254, 11
	s_mul_i32 s2, s1, s5
	s_sub_i32 s2, s0, s2
	s_add_i32 s3, s1, 1
	s_sub_i32 s4, s2, s5
	s_cmp_ge_u32 s2, s5
	s_cselect_b32 s1, s3, s1
	s_cselect_b32 s2, s4, s2
	s_add_i32 s3, s1, 1
	s_cmp_ge_u32 s2, s5
	s_cselect_b32 s96, s3, s1
	s_mul_i32 s1, s96, s5
	s_sub_i32 s0, s0, s1
	v_readlane_b32 s1, v254, 22
	s_add_i32 s0, s0, s1
	s_cmp_lt_u32 s0, 4
	s_cselect_b64 s[2:3], -1, 0
	s_lshl_b32 s4, s0, 6
	s_add_i32 s5, s4, 0xffffff00
	s_lshl_b32 s1, s96, 8
	s_add_i32 s6, s1, 0x4000
	s_lshl_b32 s7, s96, 11
	s_movk_i32 s8, 0x100
	s_movk_i32 s9, 0x800
	s_mov_b32 s10, 0
	s_cmp_lt_u32 s0, 4
	s_cselect_b32 s44, s4, s5
	s_cselect_b32 s45, s8, s9
	s_cselect_b32 s46, s6, s7
	s_cselect_b32 s47, s9, s10
	v_readfirstlane_b32 s48, v195
	v_and_b32_e32 v0, 63, v195
	v_readlane_b32 s52, v252, 3
	v_readlane_b32 s53, v252, 4
	v_readlane_b32 s54, v254, 7
	v_readlane_b32 s55, v254, 8
	v_readlane_b32 s56, v254, 9
	v_readlane_b32 s57, v254, 10
	v_readlane_b32 s58, v251, 31
	v_readlane_b32 s59, v251, 32
	s_lshr_b32 s48, s48, 6
	s_lshl_b32 s49, s48, 3
	s_add_i32 s49, s49, s44
	s_mul_i32 s1, s96, 0x1200
	s_add_i32 s4, s47, s49
	s_lshl_b32 s4, s4, 1
	s_add_i32 s1, s1, s4
	s_add_u32 s52, s52, s1
	s_addc_u32 s53, s53, 0
	s_add_i32 s1, s46, s49
	s_lshl_b32 s4, s1, 11
	s_add_u32 s58, s58, s4
	s_addc_u32 s59, s59, 0
	s_mul_i32 s50, s1, 0x1a00
	s_add_i32 s4, s49, -1
	s_max_i32 s4, s4, 0
	s_add_i32 s4, s4, s46
	s_mul_i32 s51, s4, 0x1a00
	s_add_i32 s4, s49, 8
	s_add_i32 s5, s45, -1
	s_min_i32 s4, s4, s5
	s_add_i32 s4, s4, s46
	s_mul_i32 s5, s4, 0x1a00
	v_lshlrev_b32_e32 v9, 3, v0
	v_lshlrev_b32_e32 v6, 4, v0
	v_add_u32_e32 v7, 0x1800, v6
	v_mov_b32_e32 v8, v9
	s_mov_b32 s6, 0x24000
	v_mul_lo_u32 v2, v0, s6
	v_add_u32_e32 v3, 0x9000, v2
	v_add_u32_e32 v4, 0x12000, v2
	v_add_u32_e32 v5, 0x1b000, v2
	v_add_u32_e32 v1, s50, v9
	v_add_u32_e32 v82, s51, v9
	global_load_dwordx2 v[10:11], v82, s[88:89]
	global_load_dwordx2 v[12:13], v1, s[88:89]
	v_add_u32_e32 v1, 0x1a00, v1
	global_load_dwordx2 v[14:15], v1, s[88:89]
	v_add_u32_e32 v1, 0x1a00, v1
	global_load_dwordx2 v[16:17], v1, s[88:89]
	v_add_u32_e32 v1, 0x1a00, v1
	global_load_dwordx2 v[18:19], v1, s[88:89]
	v_add_u32_e32 v1, 0x1a00, v1
	global_load_dwordx2 v[20:21], v1, s[88:89]
	v_add_u32_e32 v1, 0x1a00, v1
	global_load_dwordx2 v[22:23], v1, s[88:89]
	v_add_u32_e32 v1, 0x1a00, v1
	global_load_dwordx2 v[24:25], v1, s[88:89]
	v_add_u32_e32 v1, 0x1a00, v1
	global_load_dwordx2 v[26:27], v1, s[88:89]
	v_add_u32_e32 v82, s5, v9
	global_load_dwordx2 v[28:29], v82, s[88:89]
	global_load_dwordx4 v[46:49], v6, s[54:55]
	global_load_dwordx4 v[50:53], v6, s[54:55] offset:3072
	global_load_dwordx4 v[54:57], v7, s[54:55]
	global_load_dwordx4 v[58:61], v6, s[56:57]
	global_load_dwordx4 v[30:33], v2, s[52:53]
	global_load_dwordx4 v[34:37], v3, s[52:53]
	global_load_dwordx4 v[38:41], v4, s[52:53]
	global_load_dwordx4 v[42:45], v5, s[52:53]
	s_cmp_ge_i32 s49, 1
	s_cselect_b64 s[60:61], -1, 0
	s_add_i32 s4, s49, 8
	s_cmp_lt_i32 s4, s45
	s_cselect_b64 s[6:7], -1, 0
	s_waitcnt vmcnt(0)
	v_cndmask_b32_e64 v62, 0, v46, s[60:61]
	v_cndmask_b32_e64 v66, 0, v54, s[6:7]
	v_cndmask_b32_e64 v63, 0, v47, s[60:61]
	v_cndmask_b32_e64 v67, 0, v55, s[6:7]
	v_cndmask_b32_e64 v64, 0, v48, s[60:61]
	v_cndmask_b32_e64 v68, 0, v56, s[6:7]
	v_cndmask_b32_e64 v65, 0, v49, s[60:61]
	v_cndmask_b32_e64 v69, 0, v57, s[6:7]
	v_lshlrev_b32_e32 v70, 16, v10
	v_and_b32_e32 v71, 0xffff0000, v10
	v_lshlrev_b32_e32 v72, 16, v11
	v_and_b32_e32 v73, 0xffff0000, v11
	v_lshlrev_b32_e32 v74, 16, v12
	v_and_b32_e32 v75, 0xffff0000, v12
	v_lshlrev_b32_e32 v76, 16, v13
	v_and_b32_e32 v77, 0xffff0000, v13
	v_lshlrev_b32_e32 v78, 16, v14
	v_and_b32_e32 v79, 0xffff0000, v14
	v_lshlrev_b32_e32 v80, 16, v15
	v_and_b32_e32 v81, 0xffff0000, v15
	v_mul_f32_e32 v154, v62, v70
	v_mul_f32_e32 v155, v63, v71
	v_mul_f32_e32 v156, v64, v72
	v_mul_f32_e32 v157, v65, v73
	v_fmac_f32_e32 v154, v50, v74
	v_fmac_f32_e32 v155, v51, v75
	v_fmac_f32_e32 v156, v52, v76
	v_fmac_f32_e32 v157, v53, v77
	v_fmac_f32_e32 v154, v54, v78
	v_fmac_f32_e32 v155, v55, v79
	v_fmac_f32_e32 v156, v56, v80
	v_fmac_f32_e32 v157, v57, v81
	v_lshlrev_b32_e32 v158, 16, v30
	v_lshlrev_b32_e32 v159, 16, v34
	v_lshlrev_b32_e32 v160, 16, v38
	v_lshlrev_b32_e32 v161, 16, v42
	v_mul_f32_e32 v162, v154, v158
	v_mul_f32_e32 v163, v155, v159
	v_mul_f32_e32 v164, v156, v160
	v_mul_f32_e32 v165, v157, v161
	v_mul_f32_e32 v178, v162, v162
	v_fmac_f32_e32 v178, v163, v163
	v_fmac_f32_e32 v178, v164, v164
	v_fmac_f32_e32 v178, v165, v165
	v_lshlrev_b32_e32 v70, 16, v16
	v_and_b32_e32 v71, 0xffff0000, v16
	v_lshlrev_b32_e32 v72, 16, v17
	v_and_b32_e32 v73, 0xffff0000, v17
	v_mul_f32_e32 v154, v46, v74
	v_mul_f32_e32 v155, v47, v75
	v_mul_f32_e32 v156, v48, v76
	v_mul_f32_e32 v157, v49, v77
	v_fmac_f32_e32 v154, v50, v78
	v_fmac_f32_e32 v155, v51, v79
	v_fmac_f32_e32 v156, v52, v80
	v_fmac_f32_e32 v157, v53, v81
	v_fmac_f32_e32 v154, v54, v70
	v_fmac_f32_e32 v155, v55, v71
	v_fmac_f32_e32 v156, v56, v72
	v_fmac_f32_e32 v157, v57, v73
	v_and_b32_e32 v158, 0xffff0000, v30
	v_and_b32_e32 v159, 0xffff0000, v34
	v_and_b32_e32 v160, 0xffff0000, v38
	v_and_b32_e32 v161, 0xffff0000, v42
	v_mul_f32_e32 v166, v154, v158
	v_mul_f32_e32 v167, v155, v159
	v_mul_f32_e32 v168, v156, v160
	v_mul_f32_e32 v169, v157, v161
	v_mul_f32_e32 v179, v166, v166
; __device__ __forceinline__ bf16_t f2bf(float f) { return (bf16_t)(pack2(f, 0.f) & 0xffffu); }
; __device__ __forceinline__ float bf2f(bf16_t h) { return __uint_as_float(((unsigned)h) << 16); }
; __device__ void hy_merge_tile(unsigned char* lds, const Params& p, int l, int b, int ck) {
;     ...
;     const int tt = w + 8 * q;
;     const int tp = t0 + tt;
; #pragma unroll
;     for (int gi = 0; gi < 4; ++gi) {
;       const int c = gi * 64 + lane;
;       const int tm1 = tp - 1 >= 0 ? tp - 1 : 0, tp1 = tp + 1 < L ? tp + 1 : L - 1;
;       const float za = bf2f(z[(size_t)(rowbase + tm1) * ZS + c]);
;       const float zb = bf2f(z[(size_t)(rowbase + tp) * ZS + c]);
;       const float zc = bf2f(z[(size_t)(rowbase + tp1) * ZS + c]);
;       float x0 = wc[768 + c] * zb;
;       x0 += (tp - 1 >= 0 ? wc[c] : 0.f) * za;
;       x0 += (tp + 1 < L ? wc[1536 + c] : 0.f) * zc;
;       const float v = x0 * bf2f(yL[c * 72 + tt]);
;       const float ss = wsum(v * v, lane);
;       const float rn = rsqrtf(ss * (1.f / 64.f) + EPSF);
;       y[(size_t)(rowbase + tp) * 1024 + c] = f2bf(v * rn * gm[c]);
	v_fmac_f32_e32 v179, v167, v167
	v_fmac_f32_e32 v179, v168, v168
	v_fmac_f32_e32 v179, v169, v169
	v_lshlrev_b32_e32 v74, 16, v18
	v_and_b32_e32 v75, 0xffff0000, v18
	v_lshlrev_b32_e32 v76, 16, v19
	v_and_b32_e32 v77, 0xffff0000, v19
	v_mul_f32_e32 v154, v46, v78
	v_mul_f32_e32 v155, v47, v79
	v_mul_f32_e32 v156, v48, v80
	v_mul_f32_e32 v157, v49, v81
	v_fmac_f32_e32 v154, v50, v70
	v_fmac_f32_e32 v155, v51, v71
	v_fmac_f32_e32 v156, v52, v72
	v_fmac_f32_e32 v157, v53, v73
	v_fmac_f32_e32 v154, v54, v74
	v_fmac_f32_e32 v155, v55, v75
	v_fmac_f32_e32 v156, v56, v76
	v_fmac_f32_e32 v157, v57, v77
	v_lshlrev_b32_e32 v158, 16, v31
	v_lshlrev_b32_e32 v159, 16, v35
	v_lshlrev_b32_e32 v160, 16, v39
	v_lshlrev_b32_e32 v161, 16, v43
	v_mul_f32_e32 v170, v154, v158
	v_mul_f32_e32 v171, v155, v159
	v_mul_f32_e32 v172, v156, v160
	v_mul_f32_e32 v173, v157, v161
	v_mul_f32_e32 v180, v170, v170
	v_fmac_f32_e32 v180, v171, v171
	v_fmac_f32_e32 v180, v172, v172
	v_fmac_f32_e32 v180, v173, v173
	v_lshlrev_b32_e32 v78, 16, v20
	v_and_b32_e32 v79, 0xffff0000, v20
	v_lshlrev_b32_e32 v80, 16, v21
	v_and_b32_e32 v81, 0xffff0000, v21
	v_mul_f32_e32 v154, v46, v70
	v_mul_f32_e32 v155, v47, v71
	v_mul_f32_e32 v156, v48, v72
	v_mul_f32_e32 v157, v49, v73
	v_fmac_f32_e32 v154, v50, v74
	v_fmac_f32_e32 v155, v51, v75
	v_fmac_f32_e32 v156, v52, v76
	v_fmac_f32_e32 v157, v53, v77
	v_fmac_f32_e32 v154, v54, v78
	v_fmac_f32_e32 v155, v55, v79
	v_fmac_f32_e32 v156, v56, v80
	v_fmac_f32_e32 v157, v57, v81
	v_and_b32_e32 v158, 0xffff0000, v31
	v_and_b32_e32 v159, 0xffff0000, v35
	v_and_b32_e32 v160, 0xffff0000, v39
	v_and_b32_e32 v161, 0xffff0000, v43
	v_mul_f32_e32 v174, v154, v158
	v_mul_f32_e32 v175, v155, v159
	v_mul_f32_e32 v176, v156, v160
	v_mul_f32_e32 v177, v157, v161
	v_mul_f32_e32 v181, v174, v174
	v_fmac_f32_e32 v181, v175, v175
	v_fmac_f32_e32 v181, v176, v176
	v_fmac_f32_e32 v181, v177, v177
	s_nop 1
	v_add_f32_dpp v178, v178, v178 quad_perm:[1,0,3,2] row_mask:0xf bank_mask:0xf
	v_add_f32_dpp v179, v179, v179 quad_perm:[1,0,3,2] row_mask:0xf bank_mask:0xf
	v_add_f32_dpp v180, v180, v180 quad_perm:[1,0,3,2] row_mask:0xf bank_mask:0xf
	v_add_f32_dpp v181, v181, v181 quad_perm:[1,0,3,2] row_mask:0xf bank_mask:0xf
	v_add_f32_dpp v178, v178, v178 quad_perm:[2,3,0,1] row_mask:0xf bank_mask:0xf
	v_add_f32_dpp v179, v179, v179 quad_perm:[2,3,0,1] row_mask:0xf bank_mask:0xf
	v_add_f32_dpp v180, v180, v180 quad_perm:[2,3,0,1] row_mask:0xf bank_mask:0xf
	v_add_f32_dpp v181, v181, v181 quad_perm:[2,3,0,1] row_mask:0xf bank_mask:0xf
	v_add_f32_dpp v178, v178, v178 row_half_mirror row_mask:0xf bank_mask:0xf
	v_add_f32_dpp v179, v179, v179 row_half_mirror row_mask:0xf bank_mask:0xf
	v_add_f32_dpp v180, v180, v180 row_half_mirror row_mask:0xf bank_mask:0xf
	v_add_f32_dpp v181, v181, v181 row_half_mirror row_mask:0xf bank_mask:0xf
	v_add_f32_dpp v178, v178, v178 row_mirror row_mask:0xf bank_mask:0xf
	v_add_f32_dpp v179, v179, v179 row_mirror row_mask:0xf bank_mask:0xf
	v_add_f32_dpp v180, v180, v180 row_mirror row_mask:0xf bank_mask:0xf
	v_add_f32_dpp v181, v181, v181 row_mirror row_mask:0xf bank_mask:0xf
	v_fmamk_f32 v186, v178, 0x3c800000, v194
	v_fmamk_f32 v187, v179, 0x3c800000, v194
	v_fmamk_f32 v188, v180, 0x3c800000, v194
	v_fmamk_f32 v189, v181, 0x3c800000, v194
	v_rsq_f32_e32 v186, v186
	v_rsq_f32_e32 v187, v187
	v_rsq_f32_e32 v188, v188
	v_rsq_f32_e32 v189, v189
	s_nop 0
	v_mul_f32_e32 v162, v162, v186
	v_mul_f32_e32 v163, v163, v186
	v_mul_f32_e32 v164, v164, v186
	v_mul_f32_e32 v165, v165, v186
	v_mul_f32_e32 v166, v166, v187
	v_mul_f32_e32 v167, v167, v187
	v_mul_f32_e32 v168, v168, v187
	v_mul_f32_e32 v169, v169, v187
	v_mul_f32_e32 v170, v170, v188
	v_mul_f32_e32 v171, v171, v188
	v_mul_f32_e32 v172, v172, v188
	v_mul_f32_e32 v173, v173, v188
	v_mul_f32_e32 v174, v174, v189
	v_mul_f32_e32 v175, v175, v189
	v_mul_f32_e32 v176, v176, v189
	v_mul_f32_e32 v177, v177, v189
	v_mul_f32_e32 v162, v58, v162
	v_mul_f32_e32 v163, v59, v163
	v_mul_f32_e32 v164, v60, v164
	v_mul_f32_e32 v165, v61, v165
	v_mul_f32_e32 v166, v58, v166
	v_mul_f32_e32 v167, v59, v167
	v_mul_f32_e32 v168, v60, v168
	v_mul_f32_e32 v169, v61, v169
	v_mul_f32_e32 v170, v58, v170
	v_mul_f32_e32 v171, v59, v171
	v_mul_f32_e32 v172, v60, v172
	v_mul_f32_e32 v173, v61, v173
	v_mul_f32_e32 v174, v58, v174
	v_mul_f32_e32 v175, v59, v175
	v_mul_f32_e32 v176, v60, v176
	v_mul_f32_e32 v177, v61, v177
	v_cvt_pk_bf16_f32 v182, v162, v163
	v_cvt_pk_bf16_f32 v183, v164, v165
	global_store_dwordx2 v8, v[182:183], s[58:59]
	v_cvt_pk_bf16_f32 v182, v166, v167
	v_cvt_pk_bf16_f32 v183, v168, v169
	global_store_dwordx2 v8, v[182:183], s[58:59] offset:2048
	v_add_u32_e32 v8, 0x1000, v8
	v_cvt_pk_bf16_f32 v182, v170, v171
	v_cvt_pk_bf16_f32 v183, v172, v173
	global_store_dwordx2 v8, v[182:183], s[58:59]
	v_cvt_pk_bf16_f32 v182, v174, v175
	v_cvt_pk_bf16_f32 v183, v176, v177
	global_store_dwordx2 v8, v[182:183], s[58:59] offset:2048
	v_add_u32_e32 v8, 0x1000, v8
	v_lshlrev_b32_e32 v70, 16, v22
	v_and_b32_e32 v71, 0xffff0000, v22
	v_lshlrev_b32_e32 v72, 16, v23
	v_and_b32_e32 v73, 0xffff0000, v23
	v_mul_f32_e32 v154, v46, v74
	v_mul_f32_e32 v155, v47, v75
	v_mul_f32_e32 v156, v48, v76
	v_mul_f32_e32 v157, v49, v77
	v_fmac_f32_e32 v154, v50, v78
	v_fmac_f32_e32 v155, v51, v79
	v_fmac_f32_e32 v156, v52, v80
	v_fmac_f32_e32 v157, v53, v81
	v_fmac_f32_e32 v154, v54, v70
	v_fmac_f32_e32 v155, v55, v71
	v_fmac_f32_e32 v156, v56, v72
	v_fmac_f32_e32 v157, v57, v73
	v_lshlrev_b32_e32 v158, 16, v32
	v_lshlrev_b32_e32 v159, 16, v36
	v_lshlrev_b32_e32 v160, 16, v40
	v_lshlrev_b32_e32 v161, 16, v44
	v_mul_f32_e32 v162, v154, v158
; __device__ __forceinline__ bf16_t f2bf(float f) { return (bf16_t)(pack2(f, 0.f) & 0xffffu); }
; __device__ __forceinline__ float bf2f(bf16_t h) { return __uint_as_float(((unsigned)h) << 16); }
; __device__ void hy_merge_tile(unsigned char* lds, const Params& p, int l, int b, int ck) {
;     ...
;     const int tt = w + 8 * q;
;     const int tp = t0 + tt;
; #pragma unroll
;     for (int gi = 0; gi < 4; ++gi) {
;       const int c = gi * 64 + lane;
;       const int tm1 = tp - 1 >= 0 ? tp - 1 : 0, tp1 = tp + 1 < L ? tp + 1 : L - 1;
;       const float za = bf2f(z[(size_t)(rowbase + tm1) * ZS + c]);
;       const float zb = bf2f(z[(size_t)(rowbase + tp) * ZS + c]);
;       const float zc = bf2f(z[(size_t)(rowbase + tp1) * ZS + c]);
;       float x0 = wc[768 + c] * zb;
;       x0 += (tp - 1 >= 0 ? wc[c] : 0.f) * za;
;       x0 += (tp + 1 < L ? wc[1536 + c] : 0.f) * zc;
;       const float v = x0 * bf2f(yL[c * 72 + tt]);
;       const float ss = wsum(v * v, lane);
;       const float rn = rsqrtf(ss * (1.f / 64.f) + EPSF);
;       y[(size_t)(rowbase + tp) * 1024 + c] = f2bf(v * rn * gm[c]);
	v_mul_f32_e32 v163, v155, v159
	v_mul_f32_e32 v164, v156, v160
	v_mul_f32_e32 v165, v157, v161
	v_mul_f32_e32 v178, v162, v162
	v_fmac_f32_e32 v178, v163, v163
	v_fmac_f32_e32 v178, v164, v164
	v_fmac_f32_e32 v178, v165, v165
	v_lshlrev_b32_e32 v74, 16, v24
	v_and_b32_e32 v75, 0xffff0000, v24
	v_lshlrev_b32_e32 v76, 16, v25
	v_and_b32_e32 v77, 0xffff0000, v25
	v_mul_f32_e32 v154, v46, v78
	v_mul_f32_e32 v155, v47, v79
	v_mul_f32_e32 v156, v48, v80
	v_mul_f32_e32 v157, v49, v81
	v_fmac_f32_e32 v154, v50, v70
	v_fmac_f32_e32 v155, v51, v71
	v_fmac_f32_e32 v156, v52, v72
	v_fmac_f32_e32 v157, v53, v73
	v_fmac_f32_e32 v154, v54, v74
	v_fmac_f32_e32 v155, v55, v75
	v_fmac_f32_e32 v156, v56, v76
	v_fmac_f32_e32 v157, v57, v77
	v_and_b32_e32 v158, 0xffff0000, v32
	v_and_b32_e32 v159, 0xffff0000, v36
	v_and_b32_e32 v160, 0xffff0000, v40
	v_and_b32_e32 v161, 0xffff0000, v44
	v_mul_f32_e32 v166, v154, v158
	v_mul_f32_e32 v167, v155, v159
	v_mul_f32_e32 v168, v156, v160
	v_mul_f32_e32 v169, v157, v161
	v_mul_f32_e32 v179, v166, v166
	v_fmac_f32_e32 v179, v167, v167
	v_fmac_f32_e32 v179, v168, v168
	v_fmac_f32_e32 v179, v169, v169
	v_lshlrev_b32_e32 v78, 16, v26
	v_and_b32_e32 v79, 0xffff0000, v26
	v_lshlrev_b32_e32 v80, 16, v27
	v_and_b32_e32 v81, 0xffff0000, v27
	v_mul_f32_e32 v154, v46, v70
	v_mul_f32_e32 v155, v47, v71
	v_mul_f32_e32 v156, v48, v72
	v_mul_f32_e32 v157, v49, v73
	v_fmac_f32_e32 v154, v50, v74
	v_fmac_f32_e32 v155, v51, v75
	v_fmac_f32_e32 v156, v52, v76
	v_fmac_f32_e32 v157, v53, v77
	v_fmac_f32_e32 v154, v54, v78
	v_fmac_f32_e32 v155, v55, v79
	v_fmac_f32_e32 v156, v56, v80
	v_fmac_f32_e32 v157, v57, v81
	v_lshlrev_b32_e32 v158, 16, v33
	v_lshlrev_b32_e32 v159, 16, v37
	v_lshlrev_b32_e32 v160, 16, v41
	v_lshlrev_b32_e32 v161, 16, v45
	v_mul_f32_e32 v170, v154, v158
	v_mul_f32_e32 v171, v155, v159
	v_mul_f32_e32 v172, v156, v160
	v_mul_f32_e32 v173, v157, v161
	v_mul_f32_e32 v180, v170, v170
	v_fmac_f32_e32 v180, v171, v171
	v_fmac_f32_e32 v180, v172, v172
	v_fmac_f32_e32 v180, v173, v173
	v_lshlrev_b32_e32 v70, 16, v28
	v_and_b32_e32 v71, 0xffff0000, v28
	v_lshlrev_b32_e32 v72, 16, v29
	v_and_b32_e32 v73, 0xffff0000, v29
	v_mul_f32_e32 v154, v46, v74
	v_mul_f32_e32 v155, v47, v75
	v_mul_f32_e32 v156, v48, v76
	v_mul_f32_e32 v157, v49, v77
	v_fmac_f32_e32 v154, v50, v78
	v_fmac_f32_e32 v155, v51, v79
	v_fmac_f32_e32 v156, v52, v80
	v_fmac_f32_e32 v157, v53, v81
	v_fmac_f32_e32 v154, v66, v70
	v_fmac_f32_e32 v155, v67, v71
	v_fmac_f32_e32 v156, v68, v72
	v_fmac_f32_e32 v157, v69, v73
	v_and_b32_e32 v158, 0xffff0000, v33
	v_and_b32_e32 v159, 0xffff0000, v37
	v_and_b32_e32 v160, 0xffff0000, v41
	v_and_b32_e32 v161, 0xffff0000, v45
	v_mul_f32_e32 v174, v154, v158
	v_mul_f32_e32 v175, v155, v159
	v_mul_f32_e32 v176, v156, v160
	v_mul_f32_e32 v177, v157, v161
	v_mul_f32_e32 v181, v174, v174
	v_fmac_f32_e32 v181, v175, v175
	v_fmac_f32_e32 v181, v176, v176
	v_fmac_f32_e32 v181, v177, v177
	s_nop 1
	v_add_f32_dpp v178, v178, v178 quad_perm:[1,0,3,2] row_mask:0xf bank_mask:0xf
	v_add_f32_dpp v179, v179, v179 quad_perm:[1,0,3,2] row_mask:0xf bank_mask:0xf
	v_add_f32_dpp v180, v180, v180 quad_perm:[1,0,3,2] row_mask:0xf bank_mask:0xf
	v_add_f32_dpp v181, v181, v181 quad_perm:[1,0,3,2] row_mask:0xf bank_mask:0xf
	v_add_f32_dpp v178, v178, v178 quad_perm:[2,3,0,1] row_mask:0xf bank_mask:0xf
	v_add_f32_dpp v179, v179, v179 quad_perm:[2,3,0,1] row_mask:0xf bank_mask:0xf
	v_add_f32_dpp v180, v180, v180 quad_perm:[2,3,0,1] row_mask:0xf bank_mask:0xf
	v_add_f32_dpp v181, v181, v181 quad_perm:[2,3,0,1] row_mask:0xf bank_mask:0xf
	v_add_f32_dpp v178, v178, v178 row_half_mirror row_mask:0xf bank_mask:0xf
	v_add_f32_dpp v179, v179, v179 row_half_mirror row_mask:0xf bank_mask:0xf
	v_add_f32_dpp v180, v180, v180 row_half_mirror row_mask:0xf bank_mask:0xf
	v_add_f32_dpp v181, v181, v181 row_half_mirror row_mask:0xf bank_mask:0xf
	v_add_f32_dpp v178, v178, v178 row_mirror row_mask:0xf bank_mask:0xf
	v_add_f32_dpp v179, v179, v179 row_mirror row_mask:0xf bank_mask:0xf
	v_add_f32_dpp v180, v180, v180 row_mirror row_mask:0xf bank_mask:0xf
	v_add_f32_dpp v181, v181, v181 row_mirror row_mask:0xf bank_mask:0xf
	v_fmamk_f32 v186, v178, 0x3c800000, v194
	v_fmamk_f32 v187, v179, 0x3c800000, v194
	v_fmamk_f32 v188, v180, 0x3c800000, v194
	v_fmamk_f32 v189, v181, 0x3c800000, v194
	v_rsq_f32_e32 v186, v186
	v_rsq_f32_e32 v187, v187
	v_rsq_f32_e32 v188, v188
	v_rsq_f32_e32 v189, v189
	s_nop 0
	v_mul_f32_e32 v162, v162, v186
	v_mul_f32_e32 v163, v163, v186
	v_mul_f32_e32 v164, v164, v186
	v_mul_f32_e32 v165, v165, v186
	v_mul_f32_e32 v166, v166, v187
	v_mul_f32_e32 v167, v167, v187
	v_mul_f32_e32 v168, v168, v187
	v_mul_f32_e32 v169, v169, v187
	v_mul_f32_e32 v170, v170, v188
	v_mul_f32_e32 v171, v171, v188
	v_mul_f32_e32 v172, v172, v188
	v_mul_f32_e32 v173, v173, v188
	v_mul_f32_e32 v174, v174, v189
	v_mul_f32_e32 v175, v175, v189
	v_mul_f32_e32 v176, v176, v189
	v_mul_f32_e32 v177, v177, v189
	v_mul_f32_e32 v162, v58, v162
	v_mul_f32_e32 v163, v59, v163
	v_mul_f32_e32 v164, v60, v164
	v_mul_f32_e32 v165, v61, v165
	v_mul_f32_e32 v166, v58, v166
	v_mul_f32_e32 v167, v59, v167
	v_mul_f32_e32 v168, v60, v168
	v_mul_f32_e32 v169, v61, v169
	v_mul_f32_e32 v170, v58, v170
	v_mul_f32_e32 v171, v59, v171
	v_mul_f32_e32 v172, v60, v172
	v_mul_f32_e32 v173, v61, v173
	v_mul_f32_e32 v174, v58, v174
	v_mul_f32_e32 v175, v59, v175
	v_mul_f32_e32 v176, v60, v176
	v_mul_f32_e32 v177, v61, v177
	v_cvt_pk_bf16_f32 v182, v162, v163
	v_cvt_pk_bf16_f32 v183, v164, v165
	global_store_dwordx2 v8, v[182:183], s[58:59]
	v_cvt_pk_bf16_f32 v182, v166, v167
	v_cvt_pk_bf16_f32 v183, v168, v169
	global_store_dwordx2 v8, v[182:183], s[58:59] offset:2048
	v_add_u32_e32 v8, 0x1000, v8
	v_cvt_pk_bf16_f32 v182, v170, v171
	v_cvt_pk_bf16_f32 v183, v172, v173
	global_store_dwordx2 v8, v[182:183], s[58:59]
	v_cvt_pk_bf16_f32 v182, v174, v175
	v_cvt_pk_bf16_f32 v183, v176, v177
	global_store_dwordx2 v8, v[182:183], s[58:59] offset:2048
